# attention row-sum accumulated in two interleaved partial sums instead of one dependent chain
# baseline (speedup 1.0000x reference)
; DI void attn_item(const Params& p, int item, char* smem) {
;     ...
;   auto tile_compute = [&](int cur) {
;     const u16* Kc = Ks + cur * 64 * KSL;
;     const u16* Vc = Vs + cur * 64 * VSL;
;     f32x16 p0, p1;
; #pragma unroll
;     for (int i = 0; i < 16; ++i) { p0[i] = 0.f; p1[i] = 0.f; }
; #pragma unroll
;     for (int d0 = 0; d0 < 6; ++d0) {
;       const bf16x8 a0 = *(const bf16x8*)(Kc + r32 * KSL + d0 * 16 + hi * 8);
;       const bf16x8 a1 = *(const bf16x8*)(Kc + (32 + r32) * KSL + d0 * 16 + hi * 8);
;       p0 = __builtin_amdgcn_mfma_f32_32x32x16_bf16(a0, qr[d0], p0, 0, 0, 0);
;       p1 = __builtin_amdgcn_mfma_f32_32x32x16_bf16(a1, qr[d0], p1, 0, 0, 0);
;     }
;     float mx = p0[0];
; #pragma unroll
;     for (int i = 1; i < 16; ++i) mx = fmaxf(mx, p0[i]);
; #pragma unroll
;     for (int i = 0; i < 16; ++i) mx = fmaxf(mx, p1[i]);
;     { auto rr = __builtin_amdgcn_permlane32_swap(__float_as_uint(mx), __float_as_uint(mx), false, false);
;       mx = fmaxf(__uint_as_float(rr[0]), __uint_as_float(rr[1])); }
;     if (!__all(mx - mrun <= 8.f)) {
;       const float mn = fmaxf(mrun, mx);
;       const float alpha = __builtin_amdgcn_exp2f(mrun - mn);
;       mrun = mn; lrun *= alpha;
; #pragma unroll
;       for (int i = 0; i < 16; ++i) { o0[i] *= alpha; o1[i] *= alpha; }
;     }
;     float ps = 0.f;
; #pragma unroll
;     for (int i = 0; i < 16; ++i) { p0[i] = __builtin_amdgcn_exp2f(p0[i] - mrun); ps += p0[i]; }
; #pragma unroll
;     for (int i = 0; i < 16; ++i) { p1[i] = __builtin_amdgcn_exp2f(p1[i] - mrun); ps += p1[i]; }
;     lrun += ps;
.LBB0_531:
	ds_read_b128 v[164:167], v154
	ds_read_b128 v[168:171], v154 offset:32
	ds_read_b128 v[172:175], v154 offset:64
	ds_read_b128 v[176:179], v154 offset:96
	ds_read_b128 v[180:183], v154 offset:128
	ds_read_b128 v[184:187], v154 offset:160
	ds_read_b128 v[188:191], v154 offset:6656
	ds_read_b128 v[158:161], v154 offset:6688
	ds_read_b128 v[192:195], v154 offset:6720
	ds_read_b128 v[212:215], v154 offset:6752
	ds_read_b128 v[216:219], v154 offset:6784
	ds_read_b128 v[10:13], v154 offset:6816
	s_waitcnt lgkmcnt(11)
	v_mfma_f32_32x32x16_bf16 v[64:79], v[164:167], v[80:83], v[196:211]
	s_waitcnt lgkmcnt(10)
	v_mfma_f32_32x32x16_bf16 v[64:79], v[168:171], v[84:87], v[64:79]
	s_waitcnt lgkmcnt(9)
	v_mfma_f32_32x32x16_bf16 v[64:79], v[172:175], v[88:91], v[64:79]
	s_waitcnt lgkmcnt(8)
	v_mfma_f32_32x32x16_bf16 v[64:79], v[176:179], v[92:95], v[64:79]
	s_waitcnt lgkmcnt(7)
	v_mfma_f32_32x32x16_bf16 v[64:79], v[180:183], v[96:99], v[64:79]
	s_waitcnt lgkmcnt(6)
	v_mfma_f32_32x32x16_bf16 v[64:79], v[184:187], v[100:103], v[64:79]
	s_waitcnt lgkmcnt(5)
	v_mfma_f32_32x32x16_bf16 v[48:63], v[188:191], v[80:83], v[196:211]
	s_waitcnt lgkmcnt(4)
	v_mfma_f32_32x32x16_bf16 v[48:63], v[158:161], v[84:87], v[48:63]
	s_nop 7
	v_exp_f32_e32 v168, v64
	v_exp_f32_e32 v169, v65
	v_exp_f32_e32 v170, v66
	v_exp_f32_e32 v171, v67
	v_exp_f32_e32 v172, v68
	v_exp_f32_e32 v173, v69
	v_exp_f32_e32 v174, v70
	v_exp_f32_e32 v175, v71
	s_waitcnt lgkmcnt(3)
	v_mfma_f32_32x32x16_bf16 v[48:63], v[192:195], v[88:91], v[48:63]
	s_waitcnt lgkmcnt(2)
	v_mfma_f32_32x32x16_bf16 v[48:63], v[212:215], v[92:95], v[48:63]
	v_exp_f32_e32 v176, v72
	v_exp_f32_e32 v177, v73
	v_exp_f32_e32 v178, v74
	v_exp_f32_e32 v179, v75
	v_exp_f32_e32 v180, v76
	v_exp_f32_e32 v181, v77
	v_exp_f32_e32 v182, v78
	v_exp_f32_e32 v183, v79
	s_waitcnt lgkmcnt(1)
	v_mfma_f32_32x32x16_bf16 v[48:63], v[216:219], v[96:99], v[48:63]
	s_waitcnt lgkmcnt(0)
	v_mfma_f32_32x32x16_bf16 v[48:63], v[10:13], v[100:103], v[48:63]
	v_mov_b32_e32 v0, v168
	v_mov_b32_e32 v14, v169
	v_add_f32_e32 v0, v170, v0
	v_add_f32_e32 v14, v171, v14
	v_add_f32_e32 v0, v172, v0
	v_add_f32_e32 v14, v173, v14
	v_add_f32_e32 v0, v174, v0
	v_add_f32_e32 v14, v175, v14
	v_add_f32_e32 v0, v176, v0
	v_add_f32_e32 v14, v177, v14
	v_add_f32_e32 v0, v178, v0
	v_add_f32_e32 v14, v179, v14
	v_add_f32_e32 v0, v180, v0
	v_add_f32_e32 v14, v181, v14
	v_add_f32_e32 v0, v182, v0
	v_add_f32_e32 v14, v183, v14
	v_exp_f32_e32 v184, v48
	v_exp_f32_e32 v185, v49
	v_exp_f32_e32 v186, v50
	v_exp_f32_e32 v187, v51
	v_exp_f32_e32 v188, v52
	v_exp_f32_e32 v189, v53
	v_exp_f32_e32 v190, v54
	v_exp_f32_e32 v191, v55
	v_exp_f32_e32 v158, v56
	v_exp_f32_e32 v159, v57
	v_exp_f32_e32 v160, v58
	v_exp_f32_e32 v161, v59
	v_exp_f32_e32 v164, v60
	v_exp_f32_e32 v165, v61
	v_exp_f32_e32 v166, v62
	v_exp_f32_e32 v167, v63
	v_add_f32_e32 v0, v184, v0
	v_add_f32_e32 v14, v185, v14
	v_add_f32_e32 v0, v186, v0
	v_add_f32_e32 v14, v187, v14
	v_add_f32_e32 v0, v188, v0
	v_add_f32_e32 v14, v189, v14
	v_add_f32_e32 v0, v190, v0
	v_add_f32_e32 v14, v191, v14
	v_add_f32_e32 v0, v158, v0
	v_add_f32_e32 v14, v159, v14
	v_add_f32_e32 v0, v160, v0
	v_add_f32_e32 v14, v161, v14
	v_add_f32_e32 v0, v164, v0
	v_add_f32_e32 v14, v165, v14
	v_add_f32_e32 v0, v166, v0
	v_add_f32_e32 v14, v167, v14
	v_add_f32_e32 v0, v0, v14
	v_cmp_ge_f32_e32 vcc, s98, v0
	s_cmp_eq_u64 vcc, exec
	s_cbranch_scc1 .LBB0_533
; DI void attn_item(const Params& p, int item, char* smem) {
;     ...
;     if (!__all(mx - mrun <= 8.f)) {
;       const float mn = fmaxf(mrun, mx);
;       const float alpha = __builtin_amdgcn_exp2f(mrun - mn);
;       mrun = mn; lrun *= alpha;
; #pragma unroll
;       for (int i = 0; i < 16; ++i) { o0[i] *= alpha; o1[i] *= alpha; }
;     }
;     float ps = 0.f;
; #pragma unroll
;     for (int i = 0; i < 16; ++i) { p0[i] = __builtin_amdgcn_exp2f(p0[i] - mrun); ps += p0[i]; }
; #pragma unroll
;     for (int i = 0; i < 16; ++i) { p1[i] = __builtin_amdgcn_exp2f(p1[i] - mrun); ps += p1[i]; }
	v_max_f32_e32 v10, v64, v65
	v_max3_f32 v10, v10, v66, v67
	v_max3_f32 v10, v10, v68, v69
	v_max3_f32 v10, v10, v70, v71
	v_max3_f32 v10, v10, v72, v73
	v_max3_f32 v10, v10, v74, v75
	v_max3_f32 v10, v10, v76, v77
	v_max3_f32 v10, v10, v78, v79
	v_max3_f32 v10, v10, v48, v49
	v_max3_f32 v10, v10, v50, v51
	v_max3_f32 v10, v10, v52, v53
	v_max3_f32 v10, v10, v54, v55
	v_max3_f32 v10, v10, v56, v57
	v_max3_f32 v10, v10, v58, v59
	v_max3_f32 v10, v10, v60, v61
	v_max3_f32 v10, v10, v62, v63
	v_mov_b32_e32 v11, v10
	s_nop 1
	v_permlane32_swap_b32_e32 v10, v11
	v_max_f32_e32 v10, v10, v11
	v_max_f32_e32 v11, s99, v10
	v_max_f32_e32 v10, 0, v11
	s_mov_b32 s98, 0x46000000
	v_exp_f32_e64 v10, -v10
	s_mov_b32 s99, 0
	v_sub_f32_e32 v196, v196, v11
	v_mul_f32_e32 v157, v157, v10
	v_pk_mul_f32 v[46:47], v[46:47], v[10:11] op_sel_hi:[1,0]
	v_pk_mul_f32 v[44:45], v[44:45], v[10:11] op_sel_hi:[1,0]
	v_pk_mul_f32 v[42:43], v[42:43], v[10:11] op_sel_hi:[1,0]
	v_pk_mul_f32 v[40:41], v[40:41], v[10:11] op_sel_hi:[1,0]
	v_pk_mul_f32 v[38:39], v[38:39], v[10:11] op_sel_hi:[1,0]
	v_pk_mul_f32 v[36:37], v[36:37], v[10:11] op_sel_hi:[1,0]
	v_pk_mul_f32 v[34:35], v[34:35], v[10:11] op_sel_hi:[1,0]
	v_pk_mul_f32 v[32:33], v[32:33], v[10:11] op_sel_hi:[1,0]
	v_pk_mul_f32 v[30:31], v[30:31], v[10:11] op_sel_hi:[1,0]
	v_pk_mul_f32 v[28:29], v[28:29], v[10:11] op_sel_hi:[1,0]
	v_pk_mul_f32 v[26:27], v[26:27], v[10:11] op_sel_hi:[1,0]
	v_pk_mul_f32 v[24:25], v[24:25], v[10:11] op_sel_hi:[1,0]
	v_pk_mul_f32 v[22:23], v[22:23], v[10:11] op_sel_hi:[1,0]
	v_pk_mul_f32 v[20:21], v[20:21], v[10:11] op_sel_hi:[1,0]
	v_pk_mul_f32 v[18:19], v[18:19], v[10:11] op_sel_hi:[1,0]
	v_pk_mul_f32 v[16:17], v[16:17], v[10:11] op_sel_hi:[1,0]
	v_mov_b32_e32 v197, v196
	v_mov_b32_e32 v198, v196
	v_mov_b32_e32 v199, v196
	v_mov_b32_e32 v200, v196
	v_mov_b32_e32 v201, v196
	v_mov_b32_e32 v202, v196
	v_mov_b32_e32 v203, v196
	v_mov_b32_e32 v204, v196
	v_mov_b32_e32 v205, v196
	v_mov_b32_e32 v206, v196
	v_mov_b32_e32 v207, v196
	v_mov_b32_e32 v208, v196
	v_mov_b32_e32 v209, v196
	v_mov_b32_e32 v210, v196
	v_mov_b32_e32 v211, v196
	v_sub_f32_e32 v64, v64, v11
	v_sub_f32_e32 v65, v65, v11
	v_sub_f32_e32 v66, v66, v11
	v_sub_f32_e32 v67, v67, v11
	v_sub_f32_e32 v68, v68, v11
	v_sub_f32_e32 v69, v69, v11
	v_sub_f32_e32 v70, v70, v11
	v_sub_f32_e32 v71, v71, v11
	v_sub_f32_e32 v72, v72, v11
	v_sub_f32_e32 v73, v73, v11
	v_sub_f32_e32 v74, v74, v11
	v_sub_f32_e32 v75, v75, v11
	v_sub_f32_e32 v76, v76, v11
	v_sub_f32_e32 v77, v77, v11
	v_sub_f32_e32 v78, v78, v11
	v_sub_f32_e32 v79, v79, v11
	v_sub_f32_e32 v48, v48, v11
	v_sub_f32_e32 v49, v49, v11
	v_sub_f32_e32 v50, v50, v11
	v_sub_f32_e32 v51, v51, v11
	v_sub_f32_e32 v52, v52, v11
	v_sub_f32_e32 v53, v53, v11
	v_sub_f32_e32 v54, v54, v11
	v_sub_f32_e32 v55, v55, v11
	v_sub_f32_e32 v56, v56, v11
	v_sub_f32_e32 v57, v57, v11
	v_sub_f32_e32 v58, v58, v11
	v_sub_f32_e32 v59, v59, v11
	v_sub_f32_e32 v60, v60, v11
	v_sub_f32_e32 v61, v61, v11
	v_sub_f32_e32 v62, v62, v11
	v_sub_f32_e32 v63, v63, v11
	v_exp_f32_e32 v168, v64
	v_exp_f32_e32 v169, v65
	v_exp_f32_e32 v170, v66
	v_exp_f32_e32 v171, v67
	v_exp_f32_e32 v172, v68
	v_exp_f32_e32 v173, v69
	v_exp_f32_e32 v174, v70
	v_exp_f32_e32 v175, v71
	v_exp_f32_e32 v176, v72
	v_exp_f32_e32 v177, v73
	v_exp_f32_e32 v178, v74
	v_exp_f32_e32 v179, v75
	v_exp_f32_e32 v180, v76
	v_exp_f32_e32 v181, v77
	v_exp_f32_e32 v182, v78
	v_exp_f32_e32 v183, v79
	v_exp_f32_e32 v184, v48
	v_exp_f32_e32 v185, v49
	v_exp_f32_e32 v186, v50
	v_exp_f32_e32 v187, v51
	v_exp_f32_e32 v188, v52
	v_exp_f32_e32 v189, v53
	v_exp_f32_e32 v190, v54
	v_exp_f32_e32 v191, v55
	v_exp_f32_e32 v158, v56
	v_exp_f32_e32 v159, v57
	v_exp_f32_e32 v160, v58
	v_exp_f32_e32 v161, v59
	v_exp_f32_e32 v164, v60
	v_exp_f32_e32 v165, v61
	v_exp_f32_e32 v166, v62
	v_exp_f32_e32 v167, v63
	v_mov_b32_e32 v0, v168
	v_mov_b32_e32 v14, v169
	v_add_f32_e32 v0, v170, v0
	v_add_f32_e32 v14, v171, v14
	v_add_f32_e32 v0, v172, v0
	v_add_f32_e32 v14, v173, v14
	v_add_f32_e32 v0, v174, v0
	v_add_f32_e32 v14, v175, v14
	v_add_f32_e32 v0, v176, v0
	v_add_f32_e32 v14, v177, v14
	v_add_f32_e32 v0, v178, v0
	v_add_f32_e32 v14, v179, v14
	v_add_f32_e32 v0, v180, v0
	v_add_f32_e32 v14, v181, v14
	v_add_f32_e32 v0, v182, v0
	v_add_f32_e32 v14, v183, v14
	v_add_f32_e32 v0, v184, v0
	v_add_f32_e32 v14, v185, v14
	v_add_f32_e32 v0, v186, v0
	v_add_f32_e32 v14, v187, v14
	v_add_f32_e32 v0, v188, v0
	v_add_f32_e32 v14, v189, v14
	v_add_f32_e32 v0, v190, v0
	v_add_f32_e32 v14, v191, v14
	v_add_f32_e32 v0, v158, v0
	v_add_f32_e32 v14, v159, v14
	v_add_f32_e32 v0, v160, v0
	v_add_f32_e32 v14, v161, v14
	v_add_f32_e32 v0, v164, v0
	v_add_f32_e32 v14, v165, v14
	v_add_f32_e32 v0, v166, v0
	v_add_f32_e32 v14, v167, v14
	v_add_f32_e32 v0, v0, v14

; DI void attn_item(const Params& p, int item, char* smem) {
;     ...
;   auto tile_compute = [&](int cur) {
;     const u16* Kc = Ks + cur * 64 * KSL;
;     const u16* Vc = Vs + cur * 64 * VSL;
;     f32x16 p0, p1;
; #pragma unroll
;     for (int i = 0; i < 16; ++i) { p0[i] = 0.f; p1[i] = 0.f; }
; #pragma unroll
;     for (int d0 = 0; d0 < 6; ++d0) {
;       const bf16x8 a0 = *(const bf16x8*)(Kc + r32 * KSL + d0 * 16 + hi * 8);
;       const bf16x8 a1 = *(const bf16x8*)(Kc + (32 + r32) * KSL + d0 * 16 + hi * 8);
;       p0 = __builtin_amdgcn_mfma_f32_32x32x16_bf16(a0, qr[d0], p0, 0, 0, 0);
;       p1 = __builtin_amdgcn_mfma_f32_32x32x16_bf16(a1, qr[d0], p1, 0, 0, 0);
;     }
;     float mx = p0[0];
; #pragma unroll
;     for (int i = 1; i < 16; ++i) mx = fmaxf(mx, p0[i]);
; #pragma unroll
;     for (int i = 0; i < 16; ++i) mx = fmaxf(mx, p1[i]);
;     { auto rr = __builtin_amdgcn_permlane32_swap(__float_as_uint(mx), __float_as_uint(mx), false, false);
;       mx = fmaxf(__uint_as_float(rr[0]), __uint_as_float(rr[1])); }
;     if (!__all(mx - mrun <= 8.f)) {
;       const float mn = fmaxf(mrun, mx);
;       const float alpha = __builtin_amdgcn_exp2f(mrun - mn);
;       mrun = mn; lrun *= alpha;
; #pragma unroll
;       for (int i = 0; i < 16; ++i) { o0[i] *= alpha; o1[i] *= alpha; }
;     }
;     float ps = 0.f;
; #pragma unroll
;     for (int i = 0; i < 16; ++i) { p0[i] = __builtin_amdgcn_exp2f(p0[i] - mrun); ps += p0[i]; }
; #pragma unroll
;     for (int i = 0; i < 16; ++i) { p1[i] = __builtin_amdgcn_exp2f(p1[i] - mrun); ps += p1[i]; }
;     lrun += ps;
.LBB0_535:
	ds_read_b128 v[164:167], v154 offset:13312
	ds_read_b128 v[168:171], v154 offset:13344
	ds_read_b128 v[172:175], v154 offset:13376
	ds_read_b128 v[176:179], v154 offset:13408
	ds_read_b128 v[180:183], v154 offset:13440
	ds_read_b128 v[184:187], v154 offset:13472
	ds_read_b128 v[188:191], v154 offset:19968
	ds_read_b128 v[158:161], v154 offset:20000
	ds_read_b128 v[192:195], v154 offset:20032
	ds_read_b128 v[212:215], v154 offset:20064
	ds_read_b128 v[216:219], v154 offset:20096
	ds_read_b128 v[10:13], v154 offset:20128
	s_waitcnt lgkmcnt(11)
	v_mfma_f32_32x32x16_bf16 v[64:79], v[164:167], v[80:83], v[196:211]
	s_waitcnt lgkmcnt(10)
	v_mfma_f32_32x32x16_bf16 v[64:79], v[168:171], v[84:87], v[64:79]
	s_waitcnt lgkmcnt(9)
	v_mfma_f32_32x32x16_bf16 v[64:79], v[172:175], v[88:91], v[64:79]
	s_waitcnt lgkmcnt(8)
	v_mfma_f32_32x32x16_bf16 v[64:79], v[176:179], v[92:95], v[64:79]
	s_waitcnt lgkmcnt(7)
	v_mfma_f32_32x32x16_bf16 v[64:79], v[180:183], v[96:99], v[64:79]
	s_waitcnt lgkmcnt(6)
	v_mfma_f32_32x32x16_bf16 v[64:79], v[184:187], v[100:103], v[64:79]
	s_waitcnt lgkmcnt(5)
	v_mfma_f32_32x32x16_bf16 v[48:63], v[188:191], v[80:83], v[196:211]
	s_waitcnt lgkmcnt(4)
	v_mfma_f32_32x32x16_bf16 v[48:63], v[158:161], v[84:87], v[48:63]
	s_nop 7
	v_exp_f32_e32 v168, v64
	v_exp_f32_e32 v169, v65
	v_exp_f32_e32 v170, v66
	v_exp_f32_e32 v171, v67
	v_exp_f32_e32 v172, v68
	v_exp_f32_e32 v173, v69
	v_exp_f32_e32 v174, v70
	v_exp_f32_e32 v175, v71
	s_waitcnt lgkmcnt(3)
	v_mfma_f32_32x32x16_bf16 v[48:63], v[192:195], v[88:91], v[48:63]
	s_waitcnt lgkmcnt(2)
	v_mfma_f32_32x32x16_bf16 v[48:63], v[212:215], v[92:95], v[48:63]
	v_exp_f32_e32 v176, v72
	v_exp_f32_e32 v177, v73
	v_exp_f32_e32 v178, v74
	v_exp_f32_e32 v179, v75
	v_exp_f32_e32 v180, v76
	v_exp_f32_e32 v181, v77
	v_exp_f32_e32 v182, v78
	v_exp_f32_e32 v183, v79
	s_waitcnt lgkmcnt(1)
	v_mfma_f32_32x32x16_bf16 v[48:63], v[216:219], v[96:99], v[48:63]
	s_waitcnt lgkmcnt(0)
	v_mfma_f32_32x32x16_bf16 v[48:63], v[10:13], v[100:103], v[48:63]
	v_mov_b32_e32 v0, v168
	v_mov_b32_e32 v14, v169
	v_add_f32_e32 v0, v170, v0
	v_add_f32_e32 v14, v171, v14
	v_add_f32_e32 v0, v172, v0
	v_add_f32_e32 v14, v173, v14
	v_add_f32_e32 v0, v174, v0
	v_add_f32_e32 v14, v175, v14
	v_add_f32_e32 v0, v176, v0
	v_add_f32_e32 v14, v177, v14
	v_add_f32_e32 v0, v178, v0
	v_add_f32_e32 v14, v179, v14
	v_add_f32_e32 v0, v180, v0
	v_add_f32_e32 v14, v181, v14
	v_add_f32_e32 v0, v182, v0
	v_add_f32_e32 v14, v183, v14
	v_exp_f32_e32 v184, v48
	v_exp_f32_e32 v185, v49
	v_exp_f32_e32 v186, v50
	v_exp_f32_e32 v187, v51
	v_exp_f32_e32 v188, v52
	v_exp_f32_e32 v189, v53
	v_exp_f32_e32 v190, v54
	v_exp_f32_e32 v191, v55
	v_exp_f32_e32 v158, v56
	v_exp_f32_e32 v159, v57
	v_exp_f32_e32 v160, v58
	v_exp_f32_e32 v161, v59
	v_exp_f32_e32 v164, v60
	v_exp_f32_e32 v165, v61
	v_exp_f32_e32 v166, v62
	v_exp_f32_e32 v167, v63
	v_add_f32_e32 v0, v184, v0
	v_add_f32_e32 v14, v185, v14
	v_add_f32_e32 v0, v186, v0
	v_add_f32_e32 v14, v187, v14
	v_add_f32_e32 v0, v188, v0
	v_add_f32_e32 v14, v189, v14
	v_add_f32_e32 v0, v190, v0
	v_add_f32_e32 v14, v191, v14
	v_add_f32_e32 v0, v158, v0
	v_add_f32_e32 v14, v159, v14
	v_add_f32_e32 v0, v160, v0
	v_add_f32_e32 v14, v161, v14
	v_add_f32_e32 v0, v164, v0
	v_add_f32_e32 v14, v165, v14
	v_add_f32_e32 v0, v166, v0
	v_add_f32_e32 v14, v167, v14
	v_add_f32_e32 v0, v0, v14
	v_cmp_ge_f32_e32 vcc, s98, v0
	s_cmp_eq_u64 vcc, exec
	s_cbranch_scc1 .LBB0_537
; DI void attn_item(const Params& p, int item, char* smem) {
;     ...
;     if (!__all(mx - mrun <= 8.f)) {
;       const float mn = fmaxf(mrun, mx);
;       const float alpha = __builtin_amdgcn_exp2f(mrun - mn);
;       mrun = mn; lrun *= alpha;
; #pragma unroll
;       for (int i = 0; i < 16; ++i) { o0[i] *= alpha; o1[i] *= alpha; }
;     }
;     float ps = 0.f;
; #pragma unroll
;     for (int i = 0; i < 16; ++i) { p0[i] = __builtin_amdgcn_exp2f(p0[i] - mrun); ps += p0[i]; }
; #pragma unroll
;     for (int i = 0; i < 16; ++i) { p1[i] = __builtin_amdgcn_exp2f(p1[i] - mrun); ps += p1[i]; }
	v_max_f32_e32 v10, v64, v65
	v_max3_f32 v10, v10, v66, v67
	v_max3_f32 v10, v10, v68, v69
	v_max3_f32 v10, v10, v70, v71
	v_max3_f32 v10, v10, v72, v73
	v_max3_f32 v10, v10, v74, v75
	v_max3_f32 v10, v10, v76, v77
	v_max3_f32 v10, v10, v78, v79
	v_max3_f32 v10, v10, v48, v49
	v_max3_f32 v10, v10, v50, v51
	v_max3_f32 v10, v10, v52, v53
	v_max3_f32 v10, v10, v54, v55
	v_max3_f32 v10, v10, v56, v57
	v_max3_f32 v10, v10, v58, v59
	v_max3_f32 v10, v10, v60, v61
	v_max3_f32 v10, v10, v62, v63
	v_mov_b32_e32 v11, v10
	s_nop 1
	v_permlane32_swap_b32_e32 v10, v11
	v_max_f32_e32 v10, v10, v11
	v_max_f32_e32 v11, s99, v10
	v_max_f32_e32 v10, 0, v11
	s_mov_b32 s98, 0x46000000
	v_exp_f32_e64 v10, -v10
	s_mov_b32 s99, 0
	v_sub_f32_e32 v196, v196, v11
	v_mul_f32_e32 v157, v157, v10
	v_pk_mul_f32 v[46:47], v[46:47], v[10:11] op_sel_hi:[1,0]
	v_pk_mul_f32 v[44:45], v[44:45], v[10:11] op_sel_hi:[1,0]
	v_pk_mul_f32 v[42:43], v[42:43], v[10:11] op_sel_hi:[1,0]
	v_pk_mul_f32 v[40:41], v[40:41], v[10:11] op_sel_hi:[1,0]
	v_pk_mul_f32 v[38:39], v[38:39], v[10:11] op_sel_hi:[1,0]
	v_pk_mul_f32 v[36:37], v[36:37], v[10:11] op_sel_hi:[1,0]
	v_pk_mul_f32 v[34:35], v[34:35], v[10:11] op_sel_hi:[1,0]
	v_pk_mul_f32 v[32:33], v[32:33], v[10:11] op_sel_hi:[1,0]
	v_pk_mul_f32 v[30:31], v[30:31], v[10:11] op_sel_hi:[1,0]
	v_pk_mul_f32 v[28:29], v[28:29], v[10:11] op_sel_hi:[1,0]
	v_pk_mul_f32 v[26:27], v[26:27], v[10:11] op_sel_hi:[1,0]
	v_pk_mul_f32 v[24:25], v[24:25], v[10:11] op_sel_hi:[1,0]
	v_pk_mul_f32 v[22:23], v[22:23], v[10:11] op_sel_hi:[1,0]
	v_pk_mul_f32 v[20:21], v[20:21], v[10:11] op_sel_hi:[1,0]
	v_pk_mul_f32 v[18:19], v[18:19], v[10:11] op_sel_hi:[1,0]
	v_pk_mul_f32 v[16:17], v[16:17], v[10:11] op_sel_hi:[1,0]
	v_mov_b32_e32 v197, v196
	v_mov_b32_e32 v198, v196
	v_mov_b32_e32 v199, v196
	v_mov_b32_e32 v200, v196
	v_mov_b32_e32 v201, v196
	v_mov_b32_e32 v202, v196
	v_mov_b32_e32 v203, v196
	v_mov_b32_e32 v204, v196
	v_mov_b32_e32 v205, v196
	v_mov_b32_e32 v206, v196
	v_mov_b32_e32 v207, v196
	v_mov_b32_e32 v208, v196
	v_mov_b32_e32 v209, v196
	v_mov_b32_e32 v210, v196
	v_mov_b32_e32 v211, v196
	v_sub_f32_e32 v64, v64, v11
	v_sub_f32_e32 v65, v65, v11
	v_sub_f32_e32 v66, v66, v11
	v_sub_f32_e32 v67, v67, v11
	v_sub_f32_e32 v68, v68, v11
	v_sub_f32_e32 v69, v69, v11
	v_sub_f32_e32 v70, v70, v11
	v_sub_f32_e32 v71, v71, v11
	v_sub_f32_e32 v72, v72, v11
	v_sub_f32_e32 v73, v73, v11
	v_sub_f32_e32 v74, v74, v11
	v_sub_f32_e32 v75, v75, v11
	v_sub_f32_e32 v76, v76, v11
	v_sub_f32_e32 v77, v77, v11
	v_sub_f32_e32 v78, v78, v11
	v_sub_f32_e32 v79, v79, v11
	v_sub_f32_e32 v48, v48, v11
	v_sub_f32_e32 v49, v49, v11
	v_sub_f32_e32 v50, v50, v11
	v_sub_f32_e32 v51, v51, v11
	v_sub_f32_e32 v52, v52, v11
	v_sub_f32_e32 v53, v53, v11
	v_sub_f32_e32 v54, v54, v11
	v_sub_f32_e32 v55, v55, v11
	v_sub_f32_e32 v56, v56, v11
	v_sub_f32_e32 v57, v57, v11
	v_sub_f32_e32 v58, v58, v11
	v_sub_f32_e32 v59, v59, v11
	v_sub_f32_e32 v60, v60, v11
	v_sub_f32_e32 v61, v61, v11
	v_sub_f32_e32 v62, v62, v11
	v_sub_f32_e32 v63, v63, v11
	v_exp_f32_e32 v168, v64
	v_exp_f32_e32 v169, v65
	v_exp_f32_e32 v170, v66
	v_exp_f32_e32 v171, v67
	v_exp_f32_e32 v172, v68
	v_exp_f32_e32 v173, v69
	v_exp_f32_e32 v174, v70
	v_exp_f32_e32 v175, v71
	v_exp_f32_e32 v176, v72
	v_exp_f32_e32 v177, v73
	v_exp_f32_e32 v178, v74
	v_exp_f32_e32 v179, v75
	v_exp_f32_e32 v180, v76
	v_exp_f32_e32 v181, v77
	v_exp_f32_e32 v182, v78
	v_exp_f32_e32 v183, v79
	v_exp_f32_e32 v184, v48
	v_exp_f32_e32 v185, v49
	v_exp_f32_e32 v186, v50
	v_exp_f32_e32 v187, v51
	v_exp_f32_e32 v188, v52
	v_exp_f32_e32 v189, v53
	v_exp_f32_e32 v190, v54
	v_exp_f32_e32 v191, v55
	v_exp_f32_e32 v158, v56
	v_exp_f32_e32 v159, v57
	v_exp_f32_e32 v160, v58
	v_exp_f32_e32 v161, v59
	v_exp_f32_e32 v164, v60
	v_exp_f32_e32 v165, v61
	v_exp_f32_e32 v166, v62
	v_exp_f32_e32 v167, v63
	v_mov_b32_e32 v0, v168
	v_mov_b32_e32 v14, v169
	v_add_f32_e32 v0, v170, v0
	v_add_f32_e32 v14, v171, v14
	v_add_f32_e32 v0, v172, v0
	v_add_f32_e32 v14, v173, v14
	v_add_f32_e32 v0, v174, v0
	v_add_f32_e32 v14, v175, v14
	v_add_f32_e32 v0, v176, v0
	v_add_f32_e32 v14, v177, v14
	v_add_f32_e32 v0, v178, v0
	v_add_f32_e32 v14, v179, v14
	v_add_f32_e32 v0, v180, v0
	v_add_f32_e32 v14, v181, v14
	v_add_f32_e32 v0, v182, v0
	v_add_f32_e32 v14, v183, v14
	v_add_f32_e32 v0, v184, v0
	v_add_f32_e32 v14, v185, v14
	v_add_f32_e32 v0, v186, v0
	v_add_f32_e32 v14, v187, v14
	v_add_f32_e32 v0, v188, v0
	v_add_f32_e32 v14, v189, v14
	v_add_f32_e32 v0, v190, v0
	v_add_f32_e32 v14, v191, v14
	v_add_f32_e32 v0, v158, v0
	v_add_f32_e32 v14, v159, v14
	v_add_f32_e32 v0, v160, v0
	v_add_f32_e32 v14, v161, v14
	v_add_f32_e32 v0, v164, v0
	v_add_f32_e32 v14, v165, v14
	v_add_f32_e32 v0, v166, v0
	v_add_f32_e32 v14, v167, v14
	v_add_f32_e32 v0, v0, v14
